# fixup phase: six HALO loads issued up front unconditionally, zeroing by cndmask
# speedup vs baseline: 1.0029x; 1.0029x over previous
; __device__ __forceinline__ float silu_f(float v) { return v / (1.0f + __expf(-v)); }
; __device__ __forceinline__ void phase_fixup(const Args& a, int tid) {
;     ...
;         unpack8(*(const v4u*)hc, g0); unpack8(*(const v4u*)(hc + 128), v0);
; #pragma unroll
;         for (int e = 0; e < 8; ++e) { g1[e] = 0.f; v1[e] = 0.f; g2[e] = 0.f; v2[e] = 0.f; }
;         if (!(first && lr == 0)) { unpack8(*(const v4u*)h1, g1); unpack8(*(const v4u*)(h1 + 128), v1); }
;         if (!first) { unpack8(*(const v4u*)h2, g2); unpack8(*(const v4u*)(h2 + 128), v2); }
; #pragma unroll
;         for (int e = 0; e < 8; ++e) { const float gg = cw[j0 + e] * g2[e] + cw[NUP + j0 + e] * g1[e] + cw[2 * NUP + j0 + e] * g0[e];
;             const float vv = cw[DFF + j0 + e] * v2[e] + cw[NUP + DFF + j0 + e] * v1[e] + cw[2 * NUP + DFF + j0 + e] * v0[e];
;             o[e] = silu_f(gg) * vv; }
.LBB0_746:
	s_or_b64 exec, exec, s[4:5]
	v_ashrrev_i32_e32 v9, 31, v8
	v_lshl_add_u64 v[46:47], v[8:9], 2, s[74:75]
	v_add_co_u32_e32 v52, vcc, s34, v46
	global_load_dwordx4 v[42:45], v[46:47], off
	s_nop 0
	v_addc_co_u32_e32 v53, vcc, 0, v47, vcc
	v_add_co_u32_e32 v56, vcc, s38, v46
	global_load_dwordx4 v[52:55], v[52:53], off
	s_nop 0
	v_addc_co_u32_e32 v57, vcc, 0, v47, vcc
	v_add_co_u32_e32 v60, vcc, s30, v46
	global_load_dwordx4 v[56:59], v[56:57], off offset:2048
	s_nop 0
	v_addc_co_u32_e32 v61, vcc, 0, v47, vcc
	global_load_dwordx4 v[60:63], v[60:61], off
	v_add_co_u32_e32 v64, vcc, s35, v46
	s_waitcnt vmcnt(5)
	v_lshlrev_b32_e32 v88, 16, v4
	v_addc_co_u32_e32 v65, vcc, 0, v47, vcc
	global_load_dwordx4 v[64:67], v[64:65], off offset:2048
	v_add_co_u32_e32 v68, vcc, s39, v46
	v_and_b32_e32 v89, 0xffff0000, v4
	s_nop 0
	v_addc_co_u32_e32 v69, vcc, 0, v47, vcc
	global_load_dwordx4 v[68:71], v[68:69], off offset:2048
	s_nop 0
	global_load_dwordx4 v[72:75], v[46:47], off offset:16
	s_waitcnt vmcnt(7)
	v_cndmask_b32_e64 v104, 0, v104, s[98:99]
	v_cndmask_b32_e64 v105, 0, v105, s[98:99]
	v_cndmask_b32_e64 v106, 0, v106, s[98:99]
	v_cndmask_b32_e64 v107, 0, v107, s[98:99]
	v_cndmask_b32_e64 v108, 0, v108, s[98:99]
	v_cndmask_b32_e64 v109, 0, v109, s[98:99]
	v_cndmask_b32_e64 v110, 0, v110, s[98:99]
	v_cndmask_b32_e64 v111, 0, v111, s[98:99]
	v_cndmask_b32_e64 v112, 0, v112, s[100:101]
	v_cndmask_b32_e64 v113, 0, v113, s[100:101]
	v_cndmask_b32_e64 v114, 0, v114, s[100:101]
	v_cndmask_b32_e64 v115, 0, v115, s[100:101]
	v_cndmask_b32_e64 v116, 0, v116, s[100:101]
	v_cndmask_b32_e64 v117, 0, v117, s[100:101]
	v_cndmask_b32_e64 v118, 0, v118, s[100:101]
	v_cndmask_b32_e64 v119, 0, v119, s[100:101]
	v_lshlrev_b32_e32 v36, 16, v104
	v_and_b32_e32 v37, 0xffff0000, v104
	v_lshlrev_b32_e32 v30, 16, v105
	v_and_b32_e32 v31, 0xffff0000, v105
	v_lshlrev_b32_e32 v16, 16, v106
	v_and_b32_e32 v17, 0xffff0000, v106
	v_lshlrev_b32_e32 v12, 16, v107
	v_and_b32_e32 v13, 0xffff0000, v107
	v_lshlrev_b32_e32 v34, 16, v108
	v_and_b32_e32 v35, 0xffff0000, v108
	v_lshlrev_b32_e32 v26, 16, v109
	v_and_b32_e32 v27, 0xffff0000, v109
	v_lshlrev_b32_e32 v14, 16, v110
	v_and_b32_e32 v15, 0xffff0000, v110
	v_lshlrev_b32_e32 v10, 16, v111
	v_and_b32_e32 v11, 0xffff0000, v111
	v_lshlrev_b32_e32 v38, 16, v112
	v_and_b32_e32 v39, 0xffff0000, v112
	v_lshlrev_b32_e32 v40, 16, v113
	v_and_b32_e32 v41, 0xffff0000, v113
	v_lshlrev_b32_e32 v28, 16, v114
	v_and_b32_e32 v29, 0xffff0000, v114
	v_lshlrev_b32_e32 v20, 16, v115
	v_and_b32_e32 v21, 0xffff0000, v115
	v_lshlrev_b32_e32 v24, 16, v116
	v_and_b32_e32 v25, 0xffff0000, v116
	v_lshlrev_b32_e32 v32, 16, v117
	v_and_b32_e32 v33, 0xffff0000, v117
	v_lshlrev_b32_e32 v22, 16, v118
	v_and_b32_e32 v23, 0xffff0000, v118
	v_lshlrev_b32_e32 v18, 16, v119
	v_and_b32_e32 v19, 0xffff0000, v119
	v_lshlrev_b32_e32 v90, 16, v0
	v_and_b32_e32 v91, 0xffff0000, v0
	v_lshlrev_b32_e32 v92, 16, v5
	v_and_b32_e32 v93, 0xffff0000, v5
	v_lshlrev_b32_e32 v94, 16, v1
	v_and_b32_e32 v95, 0xffff0000, v1
	v_lshl_add_u64 v[0:1], v[46:47], 0, s[18:19]
	v_lshl_add_u64 v[4:5], v[46:47], 0, s[20:21]
	v_lshl_add_u64 v[76:77], v[46:47], 0, s[22:23]
	v_lshl_add_u64 v[80:81], v[46:47], 0, s[16:17]
	v_lshlrev_b32_e32 v96, 16, v6
	v_and_b32_e32 v97, 0xffff0000, v6
	v_lshlrev_b32_e32 v98, 16, v2
	v_and_b32_e32 v99, 0xffff0000, v2
	v_lshlrev_b32_e32 v100, 16, v7
	v_and_b32_e32 v101, 0xffff0000, v7
	v_lshlrev_b32_e32 v102, 16, v3
	v_and_b32_e32 v103, 0xffff0000, v3
	v_lshl_add_u64 v[46:47], v[46:47], 0, s[24:25]
	global_load_dwordx4 v[0:3], v[0:1], off offset:16
	s_nop 0
	global_load_dwordx4 v[4:7], v[4:5], off offset:16
	s_nop 0
	global_load_dwordx4 v[76:79], v[76:77], off offset:16
	s_nop 0
	global_load_dwordx4 v[80:83], v[80:81], off offset:16
	s_nop 0
	global_load_dwordx4 v[84:87], v[46:47], off offset:16
	v_add_u32_e32 v176, s26, v176
	v_add_u32_e32 v48, s27, v48
	v_add_u32_e32 v49, s28, v49
	s_waitcnt vmcnt(10)
	v_pk_mul_f32 v[36:37], v[36:37], v[52:53]
	v_pk_mul_f32 v[30:31], v[30:31], v[54:55]
	v_pk_fma_f32 v[36:37], v[38:39], v[42:43], v[36:37]
	v_pk_fma_f32 v[30:31], v[40:41], v[44:45], v[30:31]
	s_waitcnt vmcnt(9)
	v_pk_mul_f32 v[34:35], v[34:35], v[56:57]
	v_pk_mul_f32 v[26:27], v[26:27], v[58:59]
	s_waitcnt vmcnt(8)
	v_pk_fma_f32 v[36:37], v[60:61], v[88:89], v[36:37]
	v_pk_fma_f32 v[30:31], v[62:63], v[92:93], v[30:31]
	v_mul_f32_e32 v38, 0xbfb8aa3b, v36
	v_mul_f32_e32 v39, 0xbfb8aa3b, v37
	v_mul_f32_e32 v40, 0xbfb8aa3b, v30
	v_mul_f32_e32 v41, 0xbfb8aa3b, v31
	v_exp_f32_e32 v38, v38
	v_exp_f32_e32 v39, v39
	v_exp_f32_e32 v40, v40
	v_exp_f32_e32 v41, v41
	s_waitcnt vmcnt(7)
	v_pk_fma_f32 v[24:25], v[24:25], v[64:65], v[34:35]
	v_pk_add_f32 v[34:35], v[38:39], 1.0 op_sel_hi:[1,0]
	v_pk_fma_f32 v[26:27], v[32:33], v[66:67], v[26:27]
	v_pk_add_f32 v[38:39], v[40:41], 1.0 op_sel_hi:[1,0]
	v_div_scale_f32 v40, s[4:5], v35, v35, v37
	v_div_scale_f32 v42, s[4:5], v34, v34, v36
	v_rcp_f32_e32 v44, v40
	v_rcp_f32_e32 v45, v42
	v_div_scale_f32 v41, vcc, v37, v35, v37
	v_fma_f32 v52, -v40, v44, 1.0
	v_div_scale_f32 v46, s[42:43], v39, v39, v31
	v_fma_f32 v53, -v42, v45, 1.0
	v_fmac_f32_e32 v44, v52, v44
	v_div_scale_f32 v43, s[4:5], v36, v34, v36
	v_rcp_f32_e32 v47, v46
	v_fmac_f32_e32 v45, v53, v45
	v_mul_f32_e32 v52, v41, v44
	v_mul_f32_e32 v53, v43, v45
	v_fma_f32 v54, -v40, v52, v41
	v_fma_f32 v55, -v42, v53, v43
	v_fmac_f32_e32 v52, v54, v44
	v_fmac_f32_e32 v53, v55, v45
	v_fma_f32 v40, -v40, v52, v41
	v_fma_f32 v41, -v42, v53, v43
	v_div_fmas_f32 v40, v40, v44, v52
	s_mov_b64 vcc, s[4:5]
	v_fma_f32 v32, -v46, v47, 1.0
	v_div_fixup_f32 v35, v40, v35, v37
	v_div_fmas_f32 v37, v41, v45, v53
	v_fmac_f32_e32 v47, v32, v47
	v_div_scale_f32 v32, vcc, v31, v39, v31
	s_waitcnt vmcnt(6)
; __device__ __forceinline__ float silu_f(float v) { return v / (1.0f + __expf(-v)); }
; __device__ __forceinline__ v4u pack8(const float (&f)[8]) { v4u w; w.x = pk2(f[0], f[1]); w.y = pk2(f[2], f[3]); w.z = pk2(f[4], f[5]); w.w = pk2(f[6], f[7]); return w; }
; __device__ __forceinline__ void phase_fixup(const Args& a, int tid) {
;     ...
;     for (int item = blockIdx.x * NT + tid; item < 512 * 2 * 704; item += total) {
;         const int cg = item % 704, gl = item / 704, lr = gl & 1, G = gl >> 1, j0 = 8 * cg, uc = 256 * (j0 >> 7) + (j0 & 127);
;         const bool first = (G & 255) == 0;
;         const bf16* hc = HALO + ((size_t)G * 4 + lr) * NUP + uc;
;         const bf16* h1 = lr == 0 ? HALO + ((size_t)(G - 1) * 4 + 3) * NUP + uc : HALO + ((size_t)G * 4 + 0) * NUP + uc;
;         const bf16* h2 = lr == 0 ? HALO + ((size_t)(G - 1) * 4 + 2) * NUP + uc : HALO + ((size_t)(G - 1) * 4 + 3) * NUP + uc;
;         float g0[8], v0[8], g1[8], v1[8], g2[8], v2[8], o[8];
;         unpack8(*(const v4u*)hc, g0); unpack8(*(const v4u*)(hc + 128), v0);
; #pragma unroll
;         for (int e = 0; e < 8; ++e) { g1[e] = 0.f; v1[e] = 0.f; g2[e] = 0.f; v2[e] = 0.f; }
;         if (!(first && lr == 0)) { unpack8(*(const v4u*)h1, g1); unpack8(*(const v4u*)(h1 + 128), v1); }
;         if (!first) { unpack8(*(const v4u*)h2, g2); unpack8(*(const v4u*)(h2 + 128), v2); }
;     ...
;         for (int e = 0; e < 8; ++e) { const float gg = cw[j0 + e] * g2[e] + cw[NUP + j0 + e] * g1[e] + cw[2 * NUP + j0 + e] * g0[e];
;             const float vv = cw[DFF + j0 + e] * v2[e] + cw[NUP + DFF + j0 + e] * v1[e] + cw[2 * NUP + DFF + j0 + e] * v0[e];
;             o[e] = silu_f(gg) * vv; }
;         *(v4u*)(ACT + (size_t)(G * 64 + lr) * DFF + j0) = pack8(o);
	v_pk_fma_f32 v[24:25], v[68:69], v[90:91], v[24:25]
	v_div_fixup_f32 v34, v37, v34, v36
	v_mul_f32_e32 v33, v32, v47
	v_pk_mul_f32 v[24:25], v[24:25], v[34:35]
	v_fma_f32 v34, -v46, v33, v32
	v_fmac_f32_e32 v33, v34, v47
	v_div_scale_f32 v34, s[4:5], v38, v38, v30
	v_rcp_f32_e32 v35, v34
	v_fma_f32 v32, -v46, v33, v32
	v_div_fmas_f32 v32, v32, v47, v33
	s_waitcnt vmcnt(4)
	v_pk_mul_f32 v[0:1], v[16:17], v[0:1]
	v_div_fixup_f32 v31, v32, v39, v31
	v_fma_f32 v32, -v34, v35, 1.0
	v_pk_fma_f32 v[0:1], v[28:29], v[72:73], v[0:1]
	v_fmac_f32_e32 v35, v32, v35
	v_div_scale_f32 v32, vcc, v30, v38, v30
	s_waitcnt vmcnt(3)
	v_pk_fma_f32 v[0:1], v[4:5], v[96:97], v[0:1]
	v_mul_f32_e32 v33, v32, v35
	v_mul_f32_e32 v4, 0xbfb8aa3b, v0
	v_mul_f32_e32 v5, 0xbfb8aa3b, v1
	v_fma_f32 v36, -v34, v33, v32
	v_exp_f32_e32 v4, v4
	v_exp_f32_e32 v5, v5
	v_fmac_f32_e32 v33, v36, v35
	v_fma_f32 v32, -v34, v33, v32
	v_div_fmas_f32 v16, v32, v35, v33
	v_pk_fma_f32 v[26:27], v[70:71], v[94:95], v[26:27]
	v_div_fixup_f32 v30, v16, v38, v30
	v_pk_add_f32 v[4:5], v[4:5], 1.0 op_sel_hi:[1,0]
	v_pk_mul_f32 v[16:17], v[26:27], v[30:31]
	v_div_scale_f32 v26, s[4:5], v5, v5, v1
	v_rcp_f32_e32 v27, v26
	s_waitcnt vmcnt(1)
	v_pk_mul_f32 v[14:15], v[14:15], v[80:81]
	v_pk_mul_f32 v[2:3], v[12:13], v[2:3]
	v_pk_fma_f32 v[14:15], v[22:23], v[76:77], v[14:15]
	v_fma_f32 v22, -v26, v27, 1.0
	v_fmac_f32_e32 v27, v22, v27
	v_div_scale_f32 v22, vcc, v1, v5, v1
	v_mul_f32_e32 v23, v22, v27
	v_fma_f32 v28, -v26, v23, v22
	v_fmac_f32_e32 v23, v28, v27
	v_fma_f32 v22, -v26, v23, v22
	v_div_scale_f32 v26, s[4:5], v4, v4, v0
	v_rcp_f32_e32 v28, v26
	v_div_fmas_f32 v22, v22, v27, v23
	v_div_fixup_f32 v1, v22, v5, v1
	v_pk_fma_f32 v[2:3], v[20:21], v[74:75], v[2:3]
	v_fma_f32 v5, -v26, v28, 1.0
	v_fmac_f32_e32 v28, v5, v28
	v_div_scale_f32 v5, vcc, v0, v4, v0
	v_mul_f32_e32 v22, v5, v28
	v_pk_fma_f32 v[2:3], v[6:7], v[100:101], v[2:3]
	v_fma_f32 v23, -v26, v22, v5
	v_mul_f32_e32 v6, 0xbfb8aa3b, v2
	v_mul_f32_e32 v7, 0xbfb8aa3b, v3
	v_fmac_f32_e32 v22, v23, v28
	v_exp_f32_e32 v6, v6
	v_exp_f32_e32 v7, v7
	v_fma_f32 v5, -v26, v22, v5
	v_div_fmas_f32 v5, v5, v28, v22
	s_waitcnt vmcnt(0)
	v_pk_fma_f32 v[14:15], v[84:85], v[98:99], v[14:15]
	v_div_fixup_f32 v0, v5, v4, v0
	v_pk_mul_f32 v[4:5], v[14:15], v[0:1]
	v_pk_add_f32 v[0:1], v[6:7], 1.0 op_sel_hi:[1,0]
	v_pk_mul_f32 v[6:7], v[10:11], v[82:83]
	v_div_scale_f32 v12, s[4:5], v1, v1, v3
	v_rcp_f32_e32 v13, v12
	v_pk_fma_f32 v[6:7], v[18:19], v[78:79], v[6:7]
	v_fma_f32 v10, -v12, v13, 1.0
	v_fmac_f32_e32 v13, v10, v13
	v_div_scale_f32 v10, vcc, v3, v1, v3
	v_mul_f32_e32 v11, v10, v13
	v_fma_f32 v14, -v12, v11, v10
	v_fmac_f32_e32 v11, v14, v13
	v_fma_f32 v10, -v12, v11, v10
	v_div_scale_f32 v12, s[4:5], v0, v0, v2
	v_rcp_f32_e32 v14, v12
	v_div_fmas_f32 v10, v10, v13, v11
	v_div_fixup_f32 v1, v10, v1, v3
	v_pk_fma_f32 v[6:7], v[86:87], v[102:103], v[6:7]
	v_fma_f32 v3, -v12, v14, 1.0
	v_fmac_f32_e32 v14, v3, v14
	v_div_scale_f32 v3, vcc, v2, v0, v2
	v_mul_f32_e32 v10, v3, v14
	v_fma_f32 v11, -v12, v10, v3
	v_fmac_f32_e32 v10, v11, v14
	v_fma_f32 v3, -v12, v10, v3
	v_div_fmas_f32 v3, v3, v14, v10
	v_div_fixup_f32 v0, v3, v0, v2
	v_pk_mul_f32 v[6:7], v[6:7], v[0:1]
	v_cvt_pk_bf16_f32 v2, v4, v5
	v_cvt_pk_bf16_f32 v3, v6, v7
	v_lshl_or_b32 v6, v50, 6, v51
	v_mov_b64_e32 v[4:5], s[12:13]
	v_mad_i64_i32 v[4:5], s[4:5], v6, s40, v[4:5]
	v_cmp_lt_i32_e32 vcc, s41, v176
	v_cvt_pk_bf16_f32 v0, v24, v25
	v_cvt_pk_bf16_f32 v1, v16, v17
	v_lshl_add_u64 v[4:5], v[8:9], 1, v[4:5]
	s_or_b64 s[14:15], vcc, s[14:15]
	global_store_dwordx4 v[4:5], v[0:3], off
	s_andn2_b64 exec, exec, s[14:15]
	s_cbranch_execz .LBB0_755
.LBB0_747:
	v_mul_hi_i32 v0, v176, s29
	v_lshrrev_b32_e32 v1, 31, v0
	v_ashrrev_i32_e32 v0, 7, v0
	v_add_u32_e32 v9, v0, v1
	v_ashrrev_i32_e32 v50, 1, v9
	v_and_b32_e32 v51, 1, v9
	v_add_u32_e32 v0, -1, v50
	v_cmp_eq_u32_e32 vcc, 1, v51
	v_mul_hi_i32_i24_e32 v43, 0x16000, v0
	v_mul_i32_i24_e32 v42, 0x16000, v0
	s_and_saveexec_b64 s[4:5], vcc
	s_xor_b64 s[4:5], exec, s[4:5]
	v_mul_hi_i32_i24_e32 v1, 0x16000, v50
	v_mul_i32_i24_e32 v0, 0x16000, v50
	v_lshl_add_u64 v[18:19], s[10:11], 0, v[0:1]
	s_or_saveexec_b64 s[4:5], s[4:5]
	v_mov_b64_e32 v[44:45], 0x10800
	s_xor_b64 exec, exec, s[4:5]
	v_lshl_add_u64 v[0:1], s[10:11], 0, v[42:43]
	v_lshl_add_u64 v[18:19], v[0:1], 0, s[16:17]
	v_mov_b64_e32 v[44:45], 0xb000
	s_or_b64 exec, exec, s[4:5]
	v_mul_i32_i24_e32 v0, 0x2c0, v9
	v_lshlrev_b32_e32 v1, 3, v0
	v_sub_u32_e32 v8, v48, v1
	v_lshlrev_b32_e32 v0, 4, v0
	v_sub_u32_e32 v0, v49, v0
	v_and_b32_e32 v1, 0x78, v8
	v_and_or_b32 v46, v0, s31, v1
	v_lshl_or_b32 v0, v50, 2, v51
	v_mul_hi_i32_i24_e32 v1, 0x5800, v0
	v_mul_i32_i24_e32 v0, 0x5800, v0
	v_lshl_add_u64 v[0:1], s[10:11], 0, v[0:1]
	v_ashrrev_i32_e32 v47, 31, v46
	v_lshl_add_u64 v[0:1], v[46:47], 1, v[0:1]
	global_load_dwordx4 v[4:7], v[0:1], off
	s_nop 0
	global_load_dwordx4 v[0:3], v[0:1], off offset:256
	v_and_b32_e32 v10, 0x1ff, v9
	v_cmp_ne_u32_e64 s[98:99], 0, v10
	v_and_b32_e32 v10, 0x1fe, v9
	v_cmp_ne_u32_e64 s[100:101], 0, v10
	v_lshl_add_u64 v[14:15], v[46:47], 1, v[18:19]
	v_lshl_add_u64 v[22:23], s[10:11], 0, v[42:43]
	v_lshl_add_u64 v[22:23], v[22:23], 0, v[44:45]
	v_lshl_add_u64 v[22:23], v[46:47], 1, v[22:23]
	global_load_dwordx4 v[104:107], v[14:15], off
	global_load_dwordx4 v[108:111], v[14:15], off offset:256
	global_load_dwordx4 v[112:115], v[22:23], off
	global_load_dwordx4 v[116:119], v[22:23], off offset:256
	s_branch .LBB0_746

; __global__ void __launch_bounds__(NT, 2) fwd_kernel(Args args) {
	.amdhsa_kernel _Z10fwd_kernel4Args
		.amdhsa_group_segment_fixed_size 0
		.amdhsa_private_segment_fixed_size 0
		.amdhsa_kernarg_size 416
		.amdhsa_user_sgpr_count 2
		.amdhsa_user_sgpr_dispatch_ptr 0
		.amdhsa_user_sgpr_queue_ptr 0
		.amdhsa_user_sgpr_kernarg_segment_ptr 1
		.amdhsa_user_sgpr_dispatch_id 0
		.amdhsa_user_sgpr_kernarg_preload_length 0
		.amdhsa_user_sgpr_kernarg_preload_offset 0
		.amdhsa_user_sgpr_private_segment_size 0
		.amdhsa_uses_dynamic_stack 0
		.amdhsa_enable_private_segment 0
		.amdhsa_system_sgpr_workgroup_id_x 1
		.amdhsa_system_sgpr_workgroup_id_y 0
		.amdhsa_system_sgpr_workgroup_id_z 0
		.amdhsa_system_sgpr_workgroup_info 0
		.amdhsa_system_vgpr_workitem_id 2
		.amdhsa_next_free_vgpr 247
		.amdhsa_next_free_sgpr 102
		.amdhsa_accum_offset 248
		.amdhsa_reserve_vcc 1
		.amdhsa_float_round_mode_32 0
		.amdhsa_float_round_mode_16_64 0
		.amdhsa_float_denorm_mode_32 3
		.amdhsa_float_denorm_mode_16_64 3
		.amdhsa_dx10_clamp 1
		.amdhsa_ieee_mode 1
		.amdhsa_fp16_overflow 0
		.amdhsa_tg_split 0
		.amdhsa_exception_fp_ieee_invalid_op 0
		.amdhsa_exception_fp_denorm_src 0
		.amdhsa_exception_fp_ieee_div_zero 0
		.amdhsa_exception_fp_ieee_overflow 0
		.amdhsa_exception_fp_ieee_underflow 0
		.amdhsa_exception_fp_ieee_inexact 0
		.amdhsa_exception_int_div_zero 0
	.end_amdhsa_kernel

; __global__ void __launch_bounds__(NT, 2) fwd_kernel(Args args) {
amdhsa.kernels:
  - .agpr_count:     0
    .args:
      - .offset:         0
        .size:           160
        .value_kind:     by_value
      - .offset:         160
        .size:           4
        .value_kind:     hidden_block_count_x
      - .offset:         164
        .size:           4
        .value_kind:     hidden_block_count_y
      - .offset:         168
        .size:           4
        .value_kind:     hidden_block_count_z
      - .offset:         172
        .size:           2
        .value_kind:     hidden_group_size_x
      - .offset:         174
        .size:           2
        .value_kind:     hidden_group_size_y
      - .offset:         176
        .size:           2
        .value_kind:     hidden_group_size_z
      - .offset:         178
        .size:           2
        .value_kind:     hidden_remainder_x
      - .offset:         180
        .size:           2
        .value_kind:     hidden_remainder_y
      - .offset:         182
        .size:           2
        .value_kind:     hidden_remainder_z
      - .offset:         200
        .size:           8
        .value_kind:     hidden_global_offset_x
      - .offset:         208
        .size:           8
        .value_kind:     hidden_global_offset_y
      - .offset:         216
        .size:           8
        .value_kind:     hidden_global_offset_z
      - .offset:         224
        .size:           2
        .value_kind:     hidden_grid_dims
      - .offset:         248
        .size:           8
        .value_kind:     hidden_multigrid_sync_arg
      - .offset:         280
        .size:           4
        .value_kind:     hidden_dynamic_lds_size
    .group_segment_fixed_size: 0
    .kernarg_segment_align: 8
    .kernarg_segment_size: 416
    .language:       OpenCL C
    .language_version:
      - 2
      - 0
    .max_flat_workgroup_size: 512
    .name:           _Z10fwd_kernel4Args
    .private_segment_fixed_size: 0
    .sgpr_count:     108
    .sgpr_spill_count: 16
    .symbol:         _Z10fwd_kernel4Args.kd
    .uniform_work_group_size: 1
    .uses_dynamic_stack: false
    .vgpr_count:     247
    .vgpr_spill_count: 0
    .wavefront_size: 64
